# all 11 tail-conversion rounds on the HGRN waves (mLSTM waves go straight to the phase barrier)
# speedup vs baseline: 1.0099x; 1.0026x over previous
.LBB0_512:
	v_readlane_b32 s0, v251, 36
	v_readlane_b32 s50, v251, 47
	v_readlane_b32 s1, v251, 37
	v_readlane_b32 s51, v251, 48
	s_and_b64 s[0:1], s[50:51], s[0:1]
	v_readlane_b32 s84, v251, 42
	s_andn2_b64 vcc, exec, s[0:1]
	v_readlane_b32 s60, v251, 40
	v_readlane_b32 s62, v251, 38
	v_readlane_b32 s85, v251, 43
	v_readlane_b32 s61, v251, 41
	v_readlane_b32 s63, v251, 39
	s_cbranch_vccnz .LBB0_539
	s_movk_i32 s93, 0x2c00
	s_mov_b32 s94, 0
	s_cmpk_lt_i32 s64, 0x80
	s_cbranch_scc1 .Ltail_hgrn
	s_movk_i32 s93, 0x2c00
	s_movk_i32 s94, 0x2800
	s_branch .LBB0_539

.LBB0_536:
	s_waitcnt vmcnt(0)
	s_cmpk_gt_i32 s60, 0x2bff
	s_barrier
	s_waitcnt vmcnt(0)
	s_barrier
	s_cbranch_scc1 .LBB0_539
